# prep: masked A-matrix LDS reads issued together; block-inverse lev loops: LDS loads hoisted ahead of the dependent FMA chain
# baseline (speedup 1.0000x reference)
.LBB0_1132:
	s_or_b64 exec, exec, s[0:1]
	s_waitcnt lgkmcnt(0)
	s_barrier
	ds_read_b128 v[2:5], v151
	ds_read_b128 v[6:9], v68
	ds_read_b128 v[10:13], v151 offset:64
	ds_read_b128 v[14:17], v68 offset:64
	s_waitcnt lgkmcnt(0)
	v_mfma_f32_16x16x32_bf16 v[2:5], v[2:5], v[6:9], 0
	v_mfma_f32_16x16x32_bf16 v[2:5], v[10:13], v[14:17], v[2:5]
	ds_read_b128 v[10:13], v151 offset:128
	ds_read_b128 v[18:21], v68 offset:128
	s_waitcnt lgkmcnt(0)
	v_mfma_f32_16x16x32_bf16 v[2:5], v[10:13], v[18:21], v[2:5]
	ds_read_b128 v[10:13], v151 offset:192
	ds_read_b128 v[22:25], v68 offset:192
	s_waitcnt lgkmcnt(0)
	v_mfma_f32_16x16x32_bf16 v[2:5], v[10:13], v[22:25], v[2:5]
	s_nop 7
	ds_write_b128 v152, v[2:5] offset:54272
	ds_read_b128 v[2:5], v153
	s_waitcnt lgkmcnt(0)
	v_mfma_f32_16x16x32_bf16 v[2:5], v[2:5], v[6:9], 0
	ds_read_b128 v[6:9], v153 offset:64
	s_waitcnt lgkmcnt(0)
	v_mfma_f32_16x16x32_bf16 v[2:5], v[6:9], v[14:17], v[2:5]
	ds_read_b128 v[6:9], v153 offset:128
	s_waitcnt lgkmcnt(0)
	v_mfma_f32_16x16x32_bf16 v[2:5], v[6:9], v[18:21], v[2:5]
	ds_read_b128 v[6:9], v153 offset:192
	s_waitcnt lgkmcnt(0)
	v_mfma_f32_16x16x32_bf16 v[2:5], v[6:9], v[22:25], v[2:5]
	s_nop 7
	ds_write_b128 v154, v[2:5] offset:54272
	v_lshlrev_b64 v[2:3], 14, v[0:1]
	v_lshl_add_u64 v[6:7], v[70:71], 0, v[2:3]
	v_lshl_add_u64 v[8:9], v[72:73], 0, v[2:3]
	ds_read_b128 v[2:5], v155 offset:17408
	v_lshl_add_u64 v[10:11], v[6:7], 0, v[88:89]
	v_lshl_add_u64 v[6:7], v[6:7], 0, v[90:91]
	s_waitcnt lgkmcnt(0)
	flat_store_dwordx4 v[10:11], v[2:5]
	ds_read_b128 v[2:5], v155 offset:35840
	v_lshl_add_u64 v[10:11], v[8:9], 0, v[88:89]
	s_waitcnt lgkmcnt(0)
	flat_store_dwordx4 v[10:11], v[2:5]
	ds_read_b128 v[2:5], v156 offset:17408
	s_waitcnt lgkmcnt(0)
	flat_store_dwordx4 v[6:7], v[2:5]
	ds_read_b128 v[2:5], v156 offset:35840
	v_lshl_add_u64 v[6:7], v[8:9], 0, v[90:91]
	s_waitcnt lgkmcnt(0)
	flat_store_dwordx4 v[6:7], v[2:5]
	s_waitcnt lgkmcnt(0)
	s_barrier
	ds_read_b32 v3, v69
	ds_read_b32 v2, v107
	ds_read_b32 v8, v111
	ds_read_b32 v9, v157 offset:54272
	ds_read_b32 v10, v113
	ds_read_b32 v11, v158 offset:54272
	ds_read_b32 v12, v115
	ds_read_b32 v13, v159 offset:54272
	ds_read_b32 v14, v117
	ds_read_b32 v15, v160 offset:54272
	ds_read_b32 v16, v119
	ds_read_b32 v17, v161 offset:54272
	ds_read_b32 v18, v121
	ds_read_b32 v19, v162 offset:54272
	ds_read_b32 v20, v123
	ds_read_b32 v21, v163 offset:54272
	ds_read_b32 v22, v125
	ds_read_b32 v23, v164 offset:54272
	ds_read_b32 v24, v127
	ds_read_b32 v25, v165 offset:54272
	ds_read_b32 v26, v129
	ds_read_b32 v27, v166 offset:54272
	ds_read_b32 v28, v131
	ds_read_b32 v29, v167 offset:54272
	ds_read_b32 v30, v133
	ds_read_b32 v31, v168 offset:54272
	ds_read_b32 v32, v135
	ds_read_b32 v33, v169 offset:54272
	ds_read_b32 v34, v137
	ds_read_b32 v35, v170 offset:54272
	ds_read_b32 v36, v139
	ds_read_b32 v37, v171 offset:54272
	ds_read_b32 v38, v172 offset:54272
	ds_read_b32 v39, v141
	s_waitcnt lgkmcnt(0)
	v_mov_b32_e32 v4, 0
	v_mov_b32_e32 v5, 0
	s_and_saveexec_b64 s[0:1], s[90:91]
	s_cbranch_execz .LBB0_1134
	v_mov_b32_e32 v5, v8
	v_mov_b32_e32 v6, v9
	v_sub_f32_e32 v5, v2, v5
	v_mul_f32_e32 v5, 0x3fb8aa3b, v5
	v_exp_f32_e32 v5, v5
	v_mul_f32_e32 v6, v3, v6
	v_mul_f32_e32 v5, v6, v5
.LBB0_1134:
	s_or_b64 exec, exec, s[0:1]
	ds_write_b32 v112, v5
	v_mov_b32_e32 v5, 0
	s_and_saveexec_b64 s[0:1], s[42:43]
	s_cbranch_execz .LBB0_1136
	v_mov_b32_e32 v5, v10
	v_mov_b32_e32 v6, v11
	v_sub_f32_e32 v5, v2, v5
	v_mul_f32_e32 v5, 0x3fb8aa3b, v5
	v_exp_f32_e32 v5, v5
	v_mul_f32_e32 v6, v3, v6
	v_mul_f32_e32 v5, v6, v5
.LBB0_1136:
	s_or_b64 exec, exec, s[0:1]
	ds_write_b32 v114, v5
	s_mov_b64 s[0:1], exec
	v_readlane_b32 s54, v255, 7
	v_readlane_b32 s55, v255, 8
	s_and_b64 s[54:55], s[0:1], s[54:55]
	s_mov_b64 exec, s[54:55]
	s_cbranch_execz .LBB0_1138
	v_mov_b32_e32 v4, v12
	v_mov_b32_e32 v5, v13
	v_sub_f32_e32 v4, v2, v4
	v_mul_f32_e32 v4, 0x3fb8aa3b, v4
	v_exp_f32_e32 v4, v4
	v_mul_f32_e32 v5, v3, v5
	v_mul_f32_e32 v4, v5, v4
.LBB0_1138:
	s_or_b64 exec, exec, s[0:1]
	ds_write_b32 v116, v4
	v_mov_b32_e32 v4, 0
	v_mov_b32_e32 v5, 0
	s_and_saveexec_b64 s[0:1], s[60:61]
	s_cbranch_execz .LBB0_1140
	v_mov_b32_e32 v5, v14
	v_mov_b32_e32 v6, v15
	v_sub_f32_e32 v5, v2, v5
	v_mul_f32_e32 v5, 0x3fb8aa3b, v5
	v_exp_f32_e32 v5, v5
	v_mul_f32_e32 v6, v3, v6
	v_mul_f32_e32 v5, v6, v5
.LBB0_1140:
	s_or_b64 exec, exec, s[0:1]
	ds_write_b32 v118, v5
	s_and_saveexec_b64 s[0:1], s[62:63]
	s_cbranch_execz .LBB0_1142
	v_mov_b32_e32 v4, v16
	v_mov_b32_e32 v5, v17
	v_sub_f32_e32 v4, v2, v4
	v_mul_f32_e32 v4, 0x3fb8aa3b, v4
	v_exp_f32_e32 v4, v4
	v_mul_f32_e32 v5, v3, v5
	v_mul_f32_e32 v4, v5, v4
.LBB0_1142:
	s_or_b64 exec, exec, s[0:1]
	ds_write_b32 v120, v4
	v_mov_b32_e32 v4, 0
	v_mov_b32_e32 v5, 0
	s_and_saveexec_b64 s[0:1], s[64:65]
	s_cbranch_execz .LBB0_1144
	v_mov_b32_e32 v5, v18
	v_mov_b32_e32 v6, v19
	v_sub_f32_e32 v5, v2, v5
	v_mul_f32_e32 v5, 0x3fb8aa3b, v5
	v_exp_f32_e32 v5, v5
	v_mul_f32_e32 v6, v3, v6
	v_mul_f32_e32 v5, v6, v5
.LBB0_1144:
	s_or_b64 exec, exec, s[0:1]
	ds_write_b32 v122, v5
	s_and_saveexec_b64 s[0:1], s[44:45]
	s_cbranch_execz .LBB0_1146
	v_mov_b32_e32 v4, v20
	v_mov_b32_e32 v5, v21
	v_sub_f32_e32 v4, v2, v4
	v_mul_f32_e32 v4, 0x3fb8aa3b, v4
	v_exp_f32_e32 v4, v4
	v_mul_f32_e32 v5, v3, v5
	v_mul_f32_e32 v4, v5, v4
.LBB0_1146:
	s_or_b64 exec, exec, s[0:1]
	ds_write_b32 v124, v4
	v_mov_b32_e32 v4, 0
	v_mov_b32_e32 v5, 0
	s_and_saveexec_b64 s[0:1], s[52:53]
	s_cbranch_execz .LBB0_1148
	v_mov_b32_e32 v5, v22
	v_mov_b32_e32 v6, v23
	v_sub_f32_e32 v5, v2, v5
	v_mul_f32_e32 v5, 0x3fb8aa3b, v5
	v_exp_f32_e32 v5, v5
	v_mul_f32_e32 v6, v3, v6
	v_mul_f32_e32 v5, v6, v5
.LBB0_1148:
	s_or_b64 exec, exec, s[0:1]
	ds_write_b32 v126, v5
	s_and_saveexec_b64 s[0:1], s[68:69]
	s_cbranch_execz .LBB0_1150
	v_mov_b32_e32 v4, v24
	v_mov_b32_e32 v5, v25
	v_sub_f32_e32 v4, v2, v4
	v_mul_f32_e32 v4, 0x3fb8aa3b, v4
	v_exp_f32_e32 v4, v4
	v_mul_f32_e32 v5, v3, v5
	v_mul_f32_e32 v4, v5, v4
.LBB0_1150:
	s_or_b64 exec, exec, s[0:1]
	ds_write_b32 v128, v4
	v_mov_b32_e32 v4, 0
	v_mov_b32_e32 v5, 0
	s_and_saveexec_b64 s[0:1], s[72:73]
	s_cbranch_execz .LBB0_1152
	v_mov_b32_e32 v5, v26
	v_mov_b32_e32 v6, v27
	v_sub_f32_e32 v5, v2, v5
	v_mul_f32_e32 v5, 0x3fb8aa3b, v5
	v_exp_f32_e32 v5, v5
	v_mul_f32_e32 v6, v3, v6
	v_mul_f32_e32 v5, v6, v5
.LBB0_1152:
	s_or_b64 exec, exec, s[0:1]
	ds_write_b32 v130, v5
	s_and_saveexec_b64 s[0:1], s[70:71]
	s_cbranch_execz .LBB0_1154
	v_mov_b32_e32 v4, v28
	v_mov_b32_e32 v5, v29
	v_sub_f32_e32 v4, v2, v4
	v_mul_f32_e32 v4, 0x3fb8aa3b, v4
	v_exp_f32_e32 v4, v4
	v_mul_f32_e32 v5, v3, v5
	v_mul_f32_e32 v4, v5, v4
.LBB0_1154:
	s_or_b64 exec, exec, s[0:1]
	ds_write_b32 v132, v4
	v_mov_b32_e32 v4, 0
	v_mov_b32_e32 v5, 0
	s_and_saveexec_b64 s[0:1], s[86:87]
	s_cbranch_execz .LBB0_1156
	v_mov_b32_e32 v5, v30
	v_mov_b32_e32 v6, v31
	v_sub_f32_e32 v5, v2, v5
	v_mul_f32_e32 v5, 0x3fb8aa3b, v5
	v_exp_f32_e32 v5, v5
	v_mul_f32_e32 v6, v3, v6
	v_mul_f32_e32 v5, v6, v5
.LBB0_1156:
	s_or_b64 exec, exec, s[0:1]
	ds_write_b32 v134, v5
	s_and_saveexec_b64 s[0:1], s[76:77]
	s_cbranch_execz .LBB0_1158
	v_mov_b32_e32 v4, v32
	v_mov_b32_e32 v5, v33
	v_sub_f32_e32 v4, v2, v4
	v_mul_f32_e32 v4, 0x3fb8aa3b, v4
	v_exp_f32_e32 v4, v4
	v_mul_f32_e32 v5, v3, v5
	v_mul_f32_e32 v4, v5, v4
.LBB0_1158:
	s_or_b64 exec, exec, s[0:1]
	ds_write_b32 v136, v4
	v_mov_b32_e32 v4, 0
	v_mov_b32_e32 v5, 0
	s_and_saveexec_b64 s[0:1], s[78:79]
	s_cbranch_execz .LBB0_1160
	v_mov_b32_e32 v5, v34
	v_mov_b32_e32 v6, v35
	v_sub_f32_e32 v5, v2, v5
	v_mul_f32_e32 v5, 0x3fb8aa3b, v5
	v_exp_f32_e32 v5, v5
	v_mul_f32_e32 v6, v3, v6
	v_mul_f32_e32 v5, v6, v5
.LBB0_1160:
	s_or_b64 exec, exec, s[0:1]
	ds_write_b32 v138, v5
	s_and_saveexec_b64 s[0:1], s[40:41]
	s_cbranch_execz .LBB0_1162
	v_mov_b32_e32 v4, v36
	v_mov_b32_e32 v5, v37
	v_sub_f32_e32 v4, v2, v4
	v_mul_f32_e32 v4, 0x3fb8aa3b, v4
	v_exp_f32_e32 v4, v4
	v_mul_f32_e32 v5, v3, v5
	v_mul_f32_e32 v4, v5, v4
.LBB0_1162:
	s_or_b64 exec, exec, s[0:1]
	ds_write_b32 v140, v4
	v_mov_b32_e32 v4, 0
	s_and_saveexec_b64 s[0:1], s[58:59]
	s_cbranch_execz .LBB0_1164
	v_mov_b32_e32 v4, v38
	v_mul_f32_e32 v3, v3, v4
	v_mov_b32_e32 v4, v39
	v_sub_f32_e32 v2, v2, v4
	v_mul_f32_e32 v2, 0x3fb8aa3b, v2
	v_exp_f32_e32 v2, v2
	s_nop 0
	v_mul_f32_e32 v4, v3, v2

.LBB0_1168:
	v_lshrrev_b32_e32 v18, 2, v5
	v_lshrrev_b32_e32 v19, 4, v5
	v_and_b32_e32 v20, 64, v18
	v_ashrrev_i32_e32 v21, 9, v5
	v_and_or_b32 v22, v19, 15, v20
	v_lshlrev_b32_e32 v23, 12, v21
	v_lshlrev_b32_e32 v24, 8, v22
	v_add3_u32 v25, 0, v23, v24
	v_lshlrev_b32_e32 v26, 6, v21
	v_and_b32_e32 v27, 60, v4
	v_lshlrev_b32_e32 v28, 4, v21
	v_add3_u32 v29, 0, v26, v27
	v_add_u32_e32 v30, v28, v20
	v_add3_u32 v31, v25, v26, s29
	v_lshl_add_u32 v32, v30, 8, v29
	ds_read_b128 v[36:39], v31
	ds_read2st64_b32 v[34:35], v32 offset1:1
	ds_read2st64_b32 v[40:41], v32 offset0:2 offset1:3
	v_or_b32_e32 v33, 4, v28
	v_lshlrev_b32_e32 v42, 2, v33
	v_add_u32_e32 v43, v33, v20
	v_add3_u32 v44, v25, v42, s29
	v_lshl_add_u32 v45, v43, 8, v29
	ds_read_b128 v[48:51], v44
	ds_read2st64_b32 v[46:47], v45 offset1:1
	ds_read2st64_b32 v[52:53], v45 offset0:2 offset1:3
	v_or_b32_e32 v54, 8, v28
	v_lshlrev_b32_e32 v55, 2, v54
	v_add_u32_e32 v56, v54, v20
	v_add3_u32 v57, v25, v55, s29
	v_lshl_add_u32 v58, v56, 8, v29
	ds_read_b128 v[60:63], v57
	ds_read2st64_b32 v[92:93], v58 offset1:1
	ds_read2st64_b32 v[94:95], v58 offset0:2 offset1:3
	v_or_b32_e32 v59, 12, v28
	v_lshlrev_b32_e32 v96, 2, v59
	v_add_u32_e32 v97, v59, v20
	v_add3_u32 v98, v25, v96, s29
	v_lshl_add_u32 v99, v97, 8, v29
	ds_read_b128 v[192:195], v98
	ds_read2st64_b32 v[100:101], v99 offset1:1
	ds_read2st64_b32 v[196:197], v99 offset0:2 offset1:3
	v_add_u32_e32 v198, 0, v4
	v_add_u32_e32 v199, 0x200, v5
	s_waitcnt lgkmcnt(0)
	v_cmp_lt_i32_e64 s[0:1], s3, v5
	s_or_b64 s[94:95], s[0:1], s[94:95]
	v_fma_f32 v17, v36, v34, 0
	v_fmac_f32_e32 v17, v37, v35
	v_fmac_f32_e32 v17, v38, v40
	v_fmac_f32_e32 v17, v39, v41
	v_pk_mul_f32 v[6:7], v[48:49], v[46:47]
	s_nop 0
	v_add_f32_e32 v6, v17, v6
	v_add_f32_e32 v10, v6, v7
	v_pk_mul_f32 v[6:7], v[50:51], v[52:53]
	s_nop 0
	v_add_f32_e32 v6, v10, v6
	v_add_f32_e32 v16, v6, v7
	v_pk_mul_f32 v[6:7], v[60:61], v[92:93]
	s_nop 0
	v_add_f32_e32 v6, v16, v6
	v_add_f32_e32 v10, v6, v7
	v_pk_mul_f32 v[6:7], v[62:63], v[94:95]
	s_nop 0
	v_add_f32_e32 v6, v10, v6
	v_add_f32_e32 v16, v6, v7
	v_pk_mul_f32 v[6:7], v[192:193], v[100:101]
	s_nop 0
	v_add_f32_e32 v6, v16, v6
	v_add_f32_e32 v10, v6, v7
	v_pk_mul_f32 v[6:7], v[194:195], v[196:197]
	s_nop 0
	v_add_f32_e32 v6, v10, v6
	v_add_f32_e32 v6, v6, v7
	ds_write_b32 v198, v6 offset:54272
	v_add_u32_e32 v4, 0x800, v4
	v_mov_b32_e32 v5, v199
	s_andn2_b64 exec, exec, s[94:95]
	s_cbranch_execnz .LBB0_1168

.LBB0_1171:
	v_ashrrev_i32_e32 v33, 9, v9
	v_add_u32_e32 v34, 1, v33
	v_and_b32_e32 v35, 0xf00, v7
	v_lshl_add_u32 v36, v34, 12, 0
	v_and_b32_e32 v37, 0xfffffc3c, v8
	v_and_b32_e32 v38, 0x4000, v6
	v_lshlrev_b32_e32 v39, 6, v34
	v_add_u32_e32 v40, v36, v35
	v_add_u32_e32 v41, 0, v37
	v_add3_u32 v42, v40, v38, v39
	v_add_u32_e32 v43, 0xd400, v41
	ds_read_b128 v[44:47], v42
	ds_read_b128 v[48:51], v42 offset:16
	ds_read_b128 v[52:55], v42 offset:32
	ds_read_b128 v[56:59], v42 offset:48
	ds_read2_b32 v[60:61], v43 offset1:16
	ds_read2_b32 v[62:63], v43 offset0:32 offset1:48
	ds_read2_b32 v[92:93], v43 offset0:64 offset1:80
	v_add3_u32 v94, v36, v38, v35
	ds_read2_b32 v[96:97], v43 offset0:96 offset1:112
	ds_read2_b32 v[98:99], v43 offset0:128 offset1:144
	ds_read2_b32 v[100:101], v43 offset0:160 offset1:176
	ds_read2_b32 v[192:193], v43 offset0:192 offset1:208
	ds_read2_b32 v[194:195], v43 offset0:224 offset1:240
	v_lshlrev_b32_e32 v95, 6, v33
	v_and_b32_e32 v196, 60, v8
	v_add3_u32 v197, v94, v95, v196
	v_add_u32_e32 v198, 0x200, v9
	s_waitcnt lgkmcnt(0)
	v_cmp_lt_i32_e32 vcc, s3, v9
	v_add_u32_e32 v6, 0x8000, v6
	v_add_u32_e32 v7, 0x2000, v7
	s_or_b64 s[92:93], vcc, s[92:93]
	v_fma_f32 v26, v44, v60, 0
	v_fmac_f32_e32 v26, v45, v61
	v_fmac_f32_e32 v26, v46, v62
	v_fmac_f32_e32 v26, v47, v63
	v_pk_mul_f32 v[10:11], v[48:49], v[92:93]
	s_nop 0
	v_add_f32_e32 v10, v26, v10
	v_add_f32_e32 v12, v10, v11
	v_pk_mul_f32 v[10:11], v[50:51], v[96:97]
	s_nop 0
	v_add_f32_e32 v10, v12, v10
	v_add_f32_e32 v12, v10, v11
	v_pk_mul_f32 v[10:11], v[52:53], v[98:99]
	s_nop 0
	v_add_f32_e32 v10, v12, v10
	v_add_f32_e32 v12, v10, v11
	v_pk_mul_f32 v[10:11], v[54:55], v[100:101]
	s_nop 0
	v_add_f32_e32 v10, v12, v10
	v_add_f32_e32 v12, v10, v11
	v_pk_mul_f32 v[10:11], v[56:57], v[192:193]
	s_nop 0
	v_add_f32_e32 v10, v12, v10
	v_add_f32_e32 v12, v10, v11
	v_pk_mul_f32 v[10:11], v[58:59], v[194:195]
	s_nop 0
	v_add_f32_e32 v10, v12, v10
	v_add_f32_e32 v10, v10, v11
	v_xor_b32_e32 v10, 0x80000000, v10
	ds_write_b32 v197, v10
	v_add_u32_e32 v8, 0x800, v8
	v_mov_b32_e32 v9, v198
	s_andn2_b64 exec, exec, s[92:93]
	s_cbranch_execnz .LBB0_1171

.LBB0_1174:
	v_lshrrev_b32_e32 v20, 2, v7
	v_lshrrev_b32_e32 v21, 4, v7
	v_and_b32_e32 v22, 64, v20
	v_ashrrev_i32_e32 v23, 9, v7
	v_and_or_b32 v24, v21, 15, v22
	v_lshlrev_b32_e32 v25, 12, v23
	v_lshlrev_b32_e32 v26, 8, v24
	v_add3_u32 v27, 0, v25, v26
	v_lshlrev_b32_e32 v28, 6, v23
	v_and_b32_e32 v29, 60, v6
	v_lshlrev_b32_e32 v30, 4, v23
	v_add3_u32 v31, 0, v28, v29
	v_add_u32_e32 v32, v30, v22
	v_add3_u32 v33, v27, v28, s25
	v_lshl_add_u32 v34, v32, 8, v31
	ds_read_b128 v[36:39], v33
	ds_read2st64_b32 v[40:41], v34 offset1:1
	ds_read2st64_b32 v[42:43], v34 offset0:2 offset1:3
	v_or_b32_e32 v35, 4, v30
	v_lshlrev_b32_e32 v44, 2, v35
	v_add_u32_e32 v45, v35, v22
	v_add3_u32 v46, v27, v44, s25
	v_lshl_add_u32 v47, v45, 8, v31
	ds_read_b128 v[48:51], v46
	ds_read2st64_b32 v[52:53], v47 offset1:1
	ds_read2st64_b32 v[54:55], v47 offset0:2 offset1:3
	v_or_b32_e32 v56, 8, v30
	v_lshlrev_b32_e32 v57, 2, v56
	v_add_u32_e32 v58, v56, v22
	v_add3_u32 v59, v27, v57, s25
	v_lshl_add_u32 v60, v58, 8, v31
	ds_read_b128 v[92:95], v59
	ds_read2st64_b32 v[62:63], v60 offset1:1
	ds_read2st64_b32 v[96:97], v60 offset0:2 offset1:3
	v_or_b32_e32 v61, 12, v30
	v_lshlrev_b32_e32 v98, 2, v61
	v_add_u32_e32 v99, v61, v22
	v_add3_u32 v100, v27, v98, s25
	v_lshl_add_u32 v101, v99, 8, v31
	ds_read_b128 v[192:195], v100
	ds_read2st64_b32 v[196:197], v101 offset1:1
	ds_read2st64_b32 v[198:199], v101 offset0:2 offset1:3
	v_add_u32_e32 v200, 16, v30
	v_lshlrev_b32_e32 v201, 2, v200
	v_add_u32_e32 v202, v200, v22
	v_add3_u32 v203, v27, v201, s25
	v_lshl_add_u32 v204, v202, 8, v31
	ds_read_b128 v[224:227], v203
	ds_read2st64_b32 v[222:223], v204 offset1:1
	ds_read2st64_b32 v[228:229], v204 offset0:2 offset1:3
	v_add_u32_e32 v205, 20, v30
	v_lshlrev_b32_e32 v221, 2, v205
	v_add_u32_e32 v230, v205, v22
	v_add3_u32 v231, v27, v221, s25
	v_lshl_add_u32 v232, v230, 8, v31
	ds_read_b128 v[236:239], v231
	ds_read2st64_b32 v[234:235], v232 offset1:1
	ds_read2st64_b32 v[240:241], v232 offset0:2 offset1:3
	v_add_u32_e32 v233, 24, v30
	v_lshlrev_b32_e32 v242, 2, v233
	v_add_u32_e32 v243, v233, v22
	v_add3_u32 v244, v27, v242, s25
	v_lshl_add_u32 v245, v243, 8, v31
	ds_read2st64_b32 v[246:247], v245 offset1:1
	s_waitcnt lgkmcnt(0)
	v_cmp_lt_i32_e64 s[0:1], s3, v7
	s_or_b64 s[94:95], s[0:1], s[94:95]
	v_fma_f32 v19, v36, v40, 0
	v_fmac_f32_e32 v19, v37, v41
	v_fmac_f32_e32 v19, v38, v42
	v_fmac_f32_e32 v19, v39, v43
	v_fmac_f32_e32 v19, v48, v52
	v_fmac_f32_e32 v19, v49, v53
	v_fmac_f32_e32 v19, v50, v54
	v_fmac_f32_e32 v19, v51, v55
	v_fmac_f32_e32 v19, v92, v62
	v_fmac_f32_e32 v19, v93, v63
	v_fmac_f32_e32 v19, v94, v96
	v_fmac_f32_e32 v19, v95, v97
	v_fmac_f32_e32 v19, v192, v196
	v_fmac_f32_e32 v19, v193, v197
	v_fmac_f32_e32 v19, v194, v198
	v_fmac_f32_e32 v19, v195, v199
	v_fmac_f32_e32 v19, v224, v222
	v_fmac_f32_e32 v19, v225, v223
	v_fmac_f32_e32 v19, v226, v228
	v_fmac_f32_e32 v19, v227, v229
	v_pk_mul_f32 v[8:9], v[236:237], v[234:235]
	s_nop 0
	v_add_f32_e32 v8, v19, v8
	v_add_f32_e32 v12, v8, v9
	v_pk_mul_f32 v[8:9], v[238:239], v[240:241]
	s_nop 0
	v_add_f32_e32 v8, v12, v8
	v_add_f32_e32 v18, v8, v9
	ds_read_b128 v[8:11], v244
	s_waitcnt lgkmcnt(0)
	v_pk_mul_f32 v[8:9], v[8:9], v[246:247]
	s_nop 0
	v_add_f32_e32 v8, v18, v8
	v_add_f32_e32 v12, v8, v9
	ds_read2st64_b32 v[8:9], v245 offset0:2 offset1:3
	s_waitcnt lgkmcnt(0)
	v_pk_mul_f32 v[8:9], v[10:11], v[8:9]
	s_nop 0
	v_add_f32_e32 v8, v12, v8
	v_add_u32_e32 v12, 28, v30
	v_add_f32_e32 v18, v8, v9
	v_lshlrev_b32_e32 v8, 2, v12
	v_add_u32_e32 v12, v12, v22
	v_add3_u32 v8, v27, v8, s25
	v_lshl_add_u32 v14, v12, 8, v31
	ds_read_b128 v[8:11], v8
	ds_read2st64_b32 v[12:13], v14 offset1:1
	s_waitcnt lgkmcnt(0)
	v_pk_mul_f32 v[8:9], v[8:9], v[12:13]
	s_nop 0
	v_add_f32_e32 v8, v18, v8
	v_add_f32_e32 v12, v8, v9
	ds_read2st64_b32 v[8:9], v14 offset0:2 offset1:3
	s_waitcnt lgkmcnt(0)
	v_pk_mul_f32 v[8:9], v[10:11], v[8:9]
	s_nop 0
	v_add_f32_e32 v8, v12, v8
	v_add_f32_e32 v8, v8, v9
	v_add_u32_e32 v9, 0, v6
	ds_write_b32 v9, v8 offset:54272
	v_add_u32_e32 v8, 0x200, v7
	v_add_u32_e32 v6, 0x800, v6
	v_mov_b32_e32 v7, v8
	s_andn2_b64 exec, exec, s[94:95]
	s_cbranch_execnz .LBB0_1174

.LBB0_1177:
	v_ashrrev_i32_e32 v33, 9, v9
	v_add_u32_e32 v34, 2, v33
	v_and_b32_e32 v35, 0xf00, v7
	v_lshl_add_u32 v36, v34, 12, 0
	v_and_b32_e32 v37, 0xfffffc3c, v8
	v_and_b32_e32 v38, 0x4000, v6
	v_lshlrev_b32_e32 v39, 6, v34
	v_add_u32_e32 v40, v36, v35
	v_add_u32_e32 v41, 0, v37
	v_add3_u32 v42, v40, v38, v39
	v_add_u32_e32 v43, 0xd400, v41
	ds_read_b128 v[44:47], v42
	ds_read_b128 v[48:51], v42 offset:16
	ds_read_b128 v[52:55], v42 offset:32
	ds_read_b128 v[56:59], v42 offset:48
	ds_read2_b32 v[60:61], v43 offset1:16
	ds_read2_b32 v[62:63], v43 offset0:32 offset1:48
	ds_read2_b32 v[92:93], v43 offset0:64 offset1:80
	v_add3_u32 v94, v36, v38, v35
	ds_read2_b32 v[96:97], v43 offset0:96 offset1:112
	ds_read2_b32 v[98:99], v43 offset0:128 offset1:144
	ds_read2_b32 v[100:101], v43 offset0:160 offset1:176
	ds_read2_b32 v[192:193], v43 offset0:192 offset1:208
	ds_read2_b32 v[194:195], v43 offset0:224 offset1:240
	v_lshlrev_b32_e32 v95, 6, v33
	v_and_b32_e32 v196, 60, v8
	v_add3_u32 v197, v94, v95, v196
	v_add_u32_e32 v198, 0x200, v9
	s_waitcnt lgkmcnt(0)
	v_cmp_lt_i32_e32 vcc, s3, v9
	v_add_u32_e32 v6, 0x8000, v6
	v_add_u32_e32 v7, 0x2000, v7
	s_or_b64 s[92:93], vcc, s[92:93]
	v_fma_f32 v26, v44, v60, 0
	v_fmac_f32_e32 v26, v45, v61
	v_fmac_f32_e32 v26, v46, v62
	v_fmac_f32_e32 v26, v47, v63
	v_pk_mul_f32 v[10:11], v[48:49], v[92:93]
	s_nop 0
	v_add_f32_e32 v10, v26, v10
	v_add_f32_e32 v12, v10, v11
	v_pk_mul_f32 v[10:11], v[50:51], v[96:97]
	s_nop 0
	v_add_f32_e32 v10, v12, v10
	v_add_f32_e32 v12, v10, v11
	v_pk_mul_f32 v[10:11], v[52:53], v[98:99]
	s_nop 0
	v_add_f32_e32 v10, v12, v10
	v_add_f32_e32 v12, v10, v11
	v_pk_mul_f32 v[10:11], v[54:55], v[100:101]
	s_nop 0
	v_add_f32_e32 v10, v12, v10
	v_add_f32_e32 v12, v10, v11
	v_pk_mul_f32 v[10:11], v[56:57], v[192:193]
	s_nop 0
	v_add_f32_e32 v10, v12, v10
	v_add_f32_e32 v12, v10, v11
	v_pk_mul_f32 v[10:11], v[58:59], v[194:195]
	s_nop 0
	v_add_f32_e32 v10, v12, v10
	v_add_f32_e32 v10, v10, v11
	v_xor_b32_e32 v10, 0x80000000, v10
	ds_write_b32 v197, v10
	v_add_u32_e32 v8, 0x800, v8
	v_mov_b32_e32 v9, v198
	s_andn2_b64 exec, exec, s[92:93]
	s_cbranch_execnz .LBB0_1177

.LBB0_1180:
	v_lshrrev_b32_e32 v20, 2, v7
	v_lshrrev_b32_e32 v21, 4, v7
	v_and_b32_e32 v22, 64, v20
	v_ashrrev_i32_e32 v23, 9, v7
	v_and_or_b32 v24, v21, 15, v22
	v_lshlrev_b32_e32 v25, 12, v23
	v_lshlrev_b32_e32 v26, 8, v24
	v_add3_u32 v27, 0, v25, v26
	v_lshlrev_b32_e32 v28, 6, v23
	v_and_b32_e32 v29, 60, v6
	v_lshlrev_b32_e32 v30, 4, v23
	v_add3_u32 v31, 0, v28, v29
	v_add_u32_e32 v32, v30, v22
	v_add3_u32 v33, v27, v28, s22
	v_lshl_add_u32 v34, v32, 8, v31
	ds_read_b128 v[36:39], v33
	ds_read2st64_b32 v[40:41], v34 offset1:1
	ds_read2st64_b32 v[42:43], v34 offset0:2 offset1:3
	v_or_b32_e32 v35, 4, v30
	v_lshlrev_b32_e32 v44, 2, v35
	v_add_u32_e32 v45, v35, v22
	v_add3_u32 v46, v27, v44, s22
	v_lshl_add_u32 v47, v45, 8, v31
	ds_read_b128 v[48:51], v46
	ds_read2st64_b32 v[52:53], v47 offset1:1
	ds_read2st64_b32 v[54:55], v47 offset0:2 offset1:3
	v_or_b32_e32 v56, 8, v30
	v_lshlrev_b32_e32 v57, 2, v56
	v_add_u32_e32 v58, v56, v22
	v_add3_u32 v59, v27, v57, s22
	v_lshl_add_u32 v60, v58, 8, v31
	ds_read_b128 v[92:95], v59
	ds_read2st64_b32 v[62:63], v60 offset1:1
	ds_read2st64_b32 v[96:97], v60 offset0:2 offset1:3
	v_or_b32_e32 v61, 12, v30
	v_lshlrev_b32_e32 v98, 2, v61
	v_add_u32_e32 v99, v61, v22
	v_add3_u32 v100, v27, v98, s22
	v_lshl_add_u32 v101, v99, 8, v31
	ds_read_b128 v[192:195], v100
	ds_read2st64_b32 v[196:197], v101 offset1:1
	ds_read2st64_b32 v[198:199], v101 offset0:2 offset1:3
	v_add_u32_e32 v200, 16, v30
	v_lshlrev_b32_e32 v201, 2, v200
	v_add_u32_e32 v202, v200, v22
	v_add3_u32 v203, v27, v201, s22
	v_lshl_add_u32 v204, v202, 8, v31
	ds_read_b128 v[224:227], v203
	ds_read2st64_b32 v[222:223], v204 offset1:1
	ds_read2st64_b32 v[228:229], v204 offset0:2 offset1:3
	v_add_u32_e32 v205, 20, v30
	v_lshlrev_b32_e32 v221, 2, v205
	v_add_u32_e32 v230, v205, v22
	v_add3_u32 v231, v27, v221, s22
	v_lshl_add_u32 v232, v230, 8, v31
	ds_read_b128 v[236:239], v231
	ds_read2st64_b32 v[234:235], v232 offset1:1
	ds_read2st64_b32 v[240:241], v232 offset0:2 offset1:3
	v_add_u32_e32 v233, 24, v30
	v_lshlrev_b32_e32 v242, 2, v233
	v_add_u32_e32 v243, v233, v22
	v_add3_u32 v244, v27, v242, s22
	v_lshl_add_u32 v245, v243, 8, v31
	ds_read2st64_b32 v[246:247], v245 offset1:1
	s_waitcnt lgkmcnt(0)
	v_cmp_lt_i32_e64 s[0:1], -1, v7
	s_or_b64 s[94:95], s[0:1], s[94:95]
	v_fma_f32 v19, v36, v40, 0
	v_fmac_f32_e32 v19, v37, v41
	v_fmac_f32_e32 v19, v38, v42
	v_fmac_f32_e32 v19, v39, v43
	v_fmac_f32_e32 v19, v48, v52
	v_fmac_f32_e32 v19, v49, v53
	v_fmac_f32_e32 v19, v50, v54
	v_fmac_f32_e32 v19, v51, v55
	v_fmac_f32_e32 v19, v92, v62
	v_fmac_f32_e32 v19, v93, v63
	v_fmac_f32_e32 v19, v94, v96
	v_fmac_f32_e32 v19, v95, v97
	v_fmac_f32_e32 v19, v192, v196
	v_fmac_f32_e32 v19, v193, v197
	v_fmac_f32_e32 v19, v194, v198
	v_fmac_f32_e32 v19, v195, v199
	v_fmac_f32_e32 v19, v224, v222
	v_fmac_f32_e32 v19, v225, v223
	v_fmac_f32_e32 v19, v226, v228
	v_fmac_f32_e32 v19, v227, v229
	v_fmac_f32_e32 v19, v236, v234
	v_fmac_f32_e32 v19, v237, v235
	v_fmac_f32_e32 v19, v238, v240
	v_fmac_f32_e32 v19, v239, v241
	ds_read_b128 v[8:11], v244
	s_waitcnt lgkmcnt(0)
	v_fmac_f32_e32 v19, v8, v246
	v_fmac_f32_e32 v19, v9, v247
	ds_read2st64_b32 v[8:9], v245 offset0:2 offset1:3
	v_add_u32_e32 v12, 28, v30
	s_waitcnt lgkmcnt(0)
	v_fmac_f32_e32 v19, v10, v8
	v_lshlrev_b32_e32 v8, 2, v12
	v_add_u32_e32 v12, v12, v22
	v_add3_u32 v8, v27, v8, s22
	v_lshl_add_u32 v18, v12, 8, v31
	v_fmac_f32_e32 v19, v11, v9
	ds_read_b128 v[8:11], v8
	ds_read2st64_b32 v[12:13], v18 offset1:1
	s_waitcnt lgkmcnt(0)
	v_fmac_f32_e32 v19, v8, v12
	v_fmac_f32_e32 v19, v9, v13
	ds_read2st64_b32 v[8:9], v18 offset0:2 offset1:3
	v_add_u32_e32 v12, 32, v30
	s_waitcnt lgkmcnt(0)
	v_fmac_f32_e32 v19, v10, v8
	v_lshlrev_b32_e32 v8, 2, v12
	v_add_u32_e32 v12, v12, v22
	v_add3_u32 v8, v27, v8, s22
	v_lshl_add_u32 v18, v12, 8, v31
	v_fmac_f32_e32 v19, v11, v9
	ds_read_b128 v[8:11], v8
	ds_read2st64_b32 v[12:13], v18 offset1:1
	s_waitcnt lgkmcnt(0)
	v_fmac_f32_e32 v19, v8, v12
	v_fmac_f32_e32 v19, v9, v13
	ds_read2st64_b32 v[8:9], v18 offset0:2 offset1:3
	v_add_u32_e32 v12, 36, v30
	s_waitcnt lgkmcnt(0)
	v_fmac_f32_e32 v19, v10, v8
	v_lshlrev_b32_e32 v8, 2, v12
	v_add_u32_e32 v12, v12, v22
	v_add3_u32 v8, v27, v8, s22
	v_lshl_add_u32 v18, v12, 8, v31
	v_fmac_f32_e32 v19, v11, v9
	ds_read_b128 v[8:11], v8
	ds_read2st64_b32 v[12:13], v18 offset1:1
	s_waitcnt lgkmcnt(0)
	v_pk_mul_f32 v[8:9], v[8:9], v[12:13]
	s_nop 0
	v_add_f32_e32 v8, v19, v8
	v_add_f32_e32 v12, v8, v9
	ds_read2st64_b32 v[8:9], v18 offset0:2 offset1:3
	s_waitcnt lgkmcnt(0)
	v_pk_mul_f32 v[8:9], v[10:11], v[8:9]
	s_nop 0
	v_add_f32_e32 v8, v12, v8
	v_add_u32_e32 v12, 40, v30
	v_add_f32_e32 v18, v8, v9
	v_lshlrev_b32_e32 v8, 2, v12
	v_add_u32_e32 v12, v12, v22
	v_add3_u32 v8, v27, v8, s22
	v_lshl_add_u32 v19, v12, 8, v31
	ds_read_b128 v[8:11], v8
	ds_read2st64_b32 v[12:13], v19 offset1:1
	s_waitcnt lgkmcnt(0)
	v_pk_mul_f32 v[8:9], v[8:9], v[12:13]
	s_nop 0
	v_add_f32_e32 v8, v18, v8
	v_add_f32_e32 v12, v8, v9
	ds_read2st64_b32 v[8:9], v19 offset0:2 offset1:3
	s_waitcnt lgkmcnt(0)
	v_pk_mul_f32 v[8:9], v[10:11], v[8:9]
	s_nop 0
	v_add_f32_e32 v8, v12, v8
	v_add_u32_e32 v12, 44, v30
	v_add_f32_e32 v18, v8, v9
	v_lshlrev_b32_e32 v8, 2, v12
	v_add_u32_e32 v12, v12, v22
	v_add3_u32 v8, v27, v8, s22
	v_lshl_add_u32 v14, v12, 8, v31
	ds_read_b128 v[8:11], v8
	ds_read2st64_b32 v[12:13], v14 offset1:1
	s_waitcnt lgkmcnt(0)
	v_pk_mul_f32 v[8:9], v[8:9], v[12:13]
	s_nop 0
	v_add_f32_e32 v8, v18, v8
	v_add_f32_e32 v12, v8, v9
	ds_read2st64_b32 v[8:9], v14 offset0:2 offset1:3
	s_waitcnt lgkmcnt(0)
	v_pk_mul_f32 v[8:9], v[10:11], v[8:9]
	s_nop 0
	v_add_f32_e32 v8, v12, v8
	v_add_f32_e32 v8, v8, v9
	v_add_u32_e32 v9, 0, v6
	ds_write_b32 v9, v8 offset:54272
	v_add_u32_e32 v8, 0x200, v7
	v_add_u32_e32 v6, 0x800, v6
	v_mov_b32_e32 v7, v8
	s_andn2_b64 exec, exec, s[94:95]
	s_cbranch_execnz .LBB0_1180

.LBB0_1183:
	v_ashrrev_i32_e32 v30, 9, v6
	v_add_u32_e32 v31, 3, v30
	v_and_b32_e32 v32, 0xf00, v5
	v_lshl_add_u32 v33, v31, 12, 0
	v_and_b32_e32 v34, 0xfffffc3c, v3
	v_and_b32_e32 v35, 0x4000, v4
	v_lshlrev_b32_e32 v36, 6, v31
	v_add_u32_e32 v37, v33, v32
	v_add_u32_e32 v38, 0, v34
	v_add3_u32 v39, v37, v35, v36
	v_add_u32_e32 v40, 0xd400, v38
	ds_read_b128 v[44:47], v39
	ds_read_b128 v[48:51], v39 offset:16
	ds_read_b128 v[52:55], v39 offset:32
	ds_read_b128 v[56:59], v39 offset:48
	ds_read2_b32 v[42:43], v40 offset1:16
	v_lshlrev_b32_e32 v41, 6, v30
	ds_read2_b32 v[60:61], v40 offset0:32 offset1:48
	ds_read2_b32 v[62:63], v40 offset0:64 offset1:80
	ds_read2_b32 v[92:93], v40 offset0:96 offset1:112
	ds_read2_b32 v[94:95], v40 offset0:128 offset1:144
	ds_read2_b32 v[96:97], v40 offset0:160 offset1:176
	ds_read2_b32 v[98:99], v40 offset0:192 offset1:208
	ds_read2_b32 v[100:101], v40 offset0:224 offset1:240
	v_and_b32_e32 v192, 60, v3
	v_add3_u32 v193, v33, v35, v32
	v_add3_u32 v194, v193, v41, v192
	v_add_u32_e32 v195, 0x200, v6
	s_waitcnt lgkmcnt(0)
	v_cmp_lt_i32_e32 vcc, -1, v6
	v_add_u32_e32 v4, 0x8000, v4
	v_add_u32_e32 v5, 0x2000, v5
	v_fma_f32 v24, v44, v42, 0
	v_fmac_f32_e32 v24, v45, v43
	s_or_b64 s[92:93], vcc, s[92:93]
	v_fmac_f32_e32 v24, v46, v60
	v_fmac_f32_e32 v24, v47, v61
	v_pk_mul_f32 v[8:9], v[48:49], v[62:63]
	s_nop 0
	v_add_f32_e32 v8, v24, v8
	v_add_f32_e32 v10, v8, v9
	v_pk_mul_f32 v[8:9], v[50:51], v[92:93]
	s_nop 0
	v_add_f32_e32 v8, v10, v8
	v_add_f32_e32 v10, v8, v9
	v_pk_mul_f32 v[8:9], v[52:53], v[94:95]
	s_nop 0
	v_add_f32_e32 v8, v10, v8
	v_add_f32_e32 v10, v8, v9
	v_pk_mul_f32 v[8:9], v[54:55], v[96:97]
	s_nop 0
	v_add_f32_e32 v8, v10, v8
	v_add_f32_e32 v10, v8, v9
	v_pk_mul_f32 v[8:9], v[56:57], v[98:99]
	s_nop 0
	v_add_f32_e32 v8, v10, v8
	v_add_f32_e32 v10, v8, v9
	v_pk_mul_f32 v[8:9], v[58:59], v[100:101]
	s_nop 0
	v_add_f32_e32 v8, v10, v8
	v_add_f32_e32 v8, v8, v9
	v_xor_b32_e32 v8, 0x80000000, v8
	ds_write_b32 v194, v8
	v_add_u32_e32 v3, 0x800, v3
	v_mov_b32_e32 v6, v195
	s_andn2_b64 exec, exec, s[92:93]
	s_cbranch_execnz .LBB0_1183
